# grid barrier: unused per-XCD release counter atomic (nobody polls it since all workgroups poll the top generation word) removed from the leader path
# speedup vs baseline: 1.0886x; 1.0025x over previous
.LBB0_124:
	s_or_b64 exec, exec, s[0:1]
	s_add_i32 s0, s20, 0x900
	s_mov_b32 s1, 0
	s_lshl_b64 s[0:1], s[0:1], 2
	s_add_u32 s0, s34, s0
	s_addc_u32 s1, s35, s1
	v_mov_b32_e32 v2, 1
	v_mov_b64_e32 v[0:1], s[0:1]
	s_waitcnt vmcnt(0) lgkmcnt(0)
	s_waitcnt vmcnt(0)

.LBB0_126:
	s_or_b64 exec, exec, s[0:1]
	s_add_i32 s82, s20, 0x900
	s_lshl_b64 s[0:1], s[82:83], 2
	s_add_u32 s0, s34, s0
	s_addc_u32 s1, s35, s1
	v_mov_b64_e32 v[0:1], s[0:1]
	s_waitcnt vmcnt(0) lgkmcnt(0)
	s_waitcnt vmcnt(0)

.LBB0_314:
	s_or_b64 exec, exec, s[0:1]
	s_add_i32 s0, s20, 0x900
	s_mov_b32 s1, s83
	s_lshl_b64 s[0:1], s[0:1], 2
	s_add_u32 s0, s34, s0
	s_addc_u32 s1, s35, s1
	v_mov_b64_e32 v[0:1], s[0:1]
	s_waitcnt vmcnt(0) lgkmcnt(0)
	s_waitcnt vmcnt(0)

.LBB0_383:
	s_or_b64 exec, exec, s[0:1]
	s_add_i32 s82, s22, 0x900
	s_lshl_b64 s[0:1], s[82:83], 2
	s_add_u32 s0, s36, s0
	s_addc_u32 s1, s37, s1
	v_mov_b64_e32 v[0:1], s[0:1]
	s_waitcnt vmcnt(0) lgkmcnt(0)
	s_waitcnt vmcnt(0)
